# T waves skip v*kt term; QKV GEMM fragment reads multi-buffered; E2 job rotation chosen by physical TG_ID parity
# speedup vs baseline: 1.0091x; 1.0091x over previous
.LBB0_250:
	s_barrier
	s_waitcnt vmcnt(7)
	ds_write_b128 v148, v[0:3]
	s_waitcnt vmcnt(5)
	ds_write_b128 v148, v[4:7] offset:5120
	s_waitcnt vmcnt(4)
	ds_write_b128 v148, v[8:11] offset:10240
	s_waitcnt vmcnt(3)
	ds_write_b128 v148, v[12:15] offset:15360
	ds_write_b128 v148, v[16:19] offset:20480
	s_waitcnt vmcnt(2)
	ds_write_b128 v148, v[20:23] offset:25600
	s_waitcnt vmcnt(1)
	ds_write_b128 v148, v[24:27] offset:30720
	s_waitcnt vmcnt(0)
	ds_write_b128 v148, v[28:31] offset:35840
	v_lshl_add_u64 v[0:1], v[116:117], 0, s[6:7]
	v_lshl_add_u64 v[4:5], v[118:119], 0, s[6:7]
	v_lshl_add_u64 v[8:9], v[120:121], 0, s[6:7]
	v_lshl_add_u64 v[12:13], v[122:123], 0, s[6:7]
	v_lshl_add_u64 v[16:17], v[124:125], 0, s[6:7]
	v_lshl_add_u64 v[20:21], v[126:127], 0, s[6:7]
	v_lshl_add_u64 v[24:25], v[128:129], 0, s[6:7]
	v_lshl_add_u64 v[28:29], v[130:131], 0, s[6:7]
	s_waitcnt lgkmcnt(0)
	s_barrier
	global_load_dwordx4 v[0:3], v[0:1], off
	s_nop 0
	global_load_dwordx4 v[4:7], v[4:5], off
	s_nop 0
	global_load_dwordx4 v[8:11], v[8:9], off
	s_nop 0
	global_load_dwordx4 v[12:15], v[12:13], off
	s_nop 0
	global_load_dwordx4 v[16:19], v[16:17], off
	s_nop 0
	global_load_dwordx4 v[20:23], v[20:21], off
	s_nop 0
	global_load_dwordx4 v[24:27], v[24:25], off
	s_nop 0
	global_load_dwordx4 v[28:31], v[28:29], off
	ds_read_b128 v[150:153], v149 offset:20480
	ds_read_b128 v[158:161], v149 offset:23040
	ds_read_b128 v[162:165], v149 offset:25600
	ds_read_b128 v[166:169], v149 offset:28160
	ds_read_b128 v[154:157], v134
	ds_read_b128 v[170:173], v134 offset:2560
	ds_read_b128 v[174:177], v134 offset:5120
	ds_read_b128 v[178:181], v134 offset:7680
	ds_read_b128 v[182:185], v149 offset:20544
	ds_read_b128 v[186:189], v149 offset:23104
	ds_read_b128 v[202:205], v149 offset:25664
	ds_read_b128 v[206:209], v149 offset:28224
	s_add_u32 s6, s6, 0x80
	s_addc_u32 s7, s7, 0
	s_waitcnt lgkmcnt(7)
	v_mfma_f32_16x16x32_bf16 v[32:35], v[150:153], v[154:157], v[32:35]
	v_mfma_f32_16x16x32_bf16 v[64:67], v[158:161], v[154:157], v[64:67]
	v_mfma_f32_16x16x32_bf16 v[60:63], v[162:165], v[154:157], v[60:63]
	v_mfma_f32_16x16x32_bf16 v[56:59], v[166:169], v[154:157], v[56:59]
	ds_read_b128 v[154:157], v134 offset:64
	s_waitcnt lgkmcnt(7)
	v_mfma_f32_16x16x32_bf16 v[52:55], v[150:153], v[170:173], v[52:55]
	v_mfma_f32_16x16x32_bf16 v[48:51], v[158:161], v[170:173], v[48:51]
	v_mfma_f32_16x16x32_bf16 v[44:47], v[162:165], v[170:173], v[44:47]
	v_mfma_f32_16x16x32_bf16 v[36:39], v[166:169], v[170:173], v[36:39]
	ds_read_b128 v[170:173], v134 offset:2624
	s_waitcnt lgkmcnt(7)
	v_mfma_f32_16x16x32_bf16 v[76:79], v[150:153], v[174:177], v[76:79]
	v_mfma_f32_16x16x32_bf16 v[72:75], v[158:161], v[174:177], v[72:75]
	v_mfma_f32_16x16x32_bf16 v[68:71], v[162:165], v[174:177], v[68:71]
	v_mfma_f32_16x16x32_bf16 v[40:43], v[166:169], v[174:177], v[40:43]
	ds_read_b128 v[174:177], v134 offset:5184
	s_waitcnt lgkmcnt(7)
	v_mfma_f32_16x16x32_bf16 v[84:87], v[150:153], v[178:181], v[84:87]
	v_mfma_f32_16x16x32_bf16 v[88:91], v[158:161], v[178:181], v[88:91]
	v_mfma_f32_16x16x32_bf16 v[92:95], v[162:165], v[178:181], v[92:95]
	v_mfma_f32_16x16x32_bf16 v[80:83], v[166:169], v[178:181], v[80:83]
	ds_read_b128 v[178:181], v134 offset:7744
	s_waitcnt lgkmcnt(3)
	v_mfma_f32_16x16x32_bf16 v[32:35], v[182:185], v[154:157], v[32:35]
	v_mfma_f32_16x16x32_bf16 v[64:67], v[186:189], v[154:157], v[64:67]
	v_mfma_f32_16x16x32_bf16 v[60:63], v[202:205], v[154:157], v[60:63]
	v_mfma_f32_16x16x32_bf16 v[56:59], v[206:209], v[154:157], v[56:59]
	s_waitcnt lgkmcnt(2)
	v_mfma_f32_16x16x32_bf16 v[52:55], v[182:185], v[170:173], v[52:55]
	v_mfma_f32_16x16x32_bf16 v[48:51], v[186:189], v[170:173], v[48:51]
	v_mfma_f32_16x16x32_bf16 v[44:47], v[202:205], v[170:173], v[44:47]
	v_mfma_f32_16x16x32_bf16 v[36:39], v[206:209], v[170:173], v[36:39]
	s_waitcnt lgkmcnt(1)
	v_mfma_f32_16x16x32_bf16 v[76:79], v[182:185], v[174:177], v[76:79]
	v_mfma_f32_16x16x32_bf16 v[72:75], v[186:189], v[174:177], v[72:75]
	v_mfma_f32_16x16x32_bf16 v[68:71], v[202:205], v[174:177], v[68:71]
	v_mfma_f32_16x16x32_bf16 v[40:43], v[206:209], v[174:177], v[40:43]
	s_waitcnt lgkmcnt(0)
	v_mfma_f32_16x16x32_bf16 v[84:87], v[182:185], v[178:181], v[84:87]
	v_mfma_f32_16x16x32_bf16 v[88:91], v[186:189], v[178:181], v[88:91]
	v_mfma_f32_16x16x32_bf16 v[92:95], v[202:205], v[178:181], v[92:95]
	v_mfma_f32_16x16x32_bf16 v[80:83], v[206:209], v[178:181], v[80:83]
	s_cmpk_eq_i32 s6, 0x780
	s_cbranch_scc0 .LBB0_250
	s_barrier
	s_waitcnt vmcnt(7)
	ds_write_b128 v148, v[0:3]
	s_waitcnt vmcnt(6)
	ds_write_b128 v148, v[4:7] offset:5120
	s_waitcnt vmcnt(5)
	ds_write_b128 v148, v[8:11] offset:10240
	s_waitcnt vmcnt(4)
	ds_write_b128 v148, v[12:15] offset:15360
	s_waitcnt vmcnt(3)
	ds_write_b128 v148, v[16:19] offset:20480
	s_waitcnt vmcnt(2)
	ds_write_b128 v148, v[20:23] offset:25600
	s_waitcnt vmcnt(1)
	ds_write_b128 v148, v[24:27] offset:30720
	s_waitcnt vmcnt(0)
	ds_write_b128 v148, v[28:31] offset:35840
	s_waitcnt lgkmcnt(0)
	s_barrier
	ds_read_b128 v[0:3], v149 offset:20480
	ds_read_b128 v[4:7], v134
	ds_read_b128 v[12:15], v149 offset:23040
	ds_read_b128 v[20:23], v149 offset:25600
	ds_read_b128 v[28:31], v149 offset:28160
	s_cmpk_lt_u32 s2, 0x800
	s_waitcnt lgkmcnt(3)
	v_mfma_f32_16x16x32_bf16 v[8:11], v[0:3], v[4:7], v[32:35]
	s_cselect_b64 s[6:7], -1, 0
	ds_read_b128 v[128:131], v149 offset:28224
	s_waitcnt lgkmcnt(3)
	v_mfma_f32_16x16x32_bf16 v[16:19], v[12:15], v[4:7], v[64:67]
	s_waitcnt lgkmcnt(2)
	v_mfma_f32_16x16x32_bf16 v[24:27], v[20:23], v[4:7], v[60:63]
	s_waitcnt lgkmcnt(1)
	v_mfma_f32_16x16x32_bf16 v[32:35], v[28:31], v[4:7], v[56:59]
	ds_read_b128 v[4:7], v134 offset:2560
	s_waitcnt lgkmcnt(0)
	v_mfma_f32_16x16x32_bf16 v[64:67], v[0:3], v[4:7], v[52:55]
	v_mfma_f32_16x16x32_bf16 v[116:119], v[12:15], v[4:7], v[48:51]
	v_mfma_f32_16x16x32_bf16 v[120:123], v[20:23], v[4:7], v[44:47]
	v_mfma_f32_16x16x32_bf16 v[36:39], v[28:31], v[4:7], v[36:39]
	ds_read_b128 v[4:7], v134 offset:5120
	s_waitcnt lgkmcnt(0)
	v_mfma_f32_16x16x32_bf16 v[124:127], v[28:31], v[4:7], v[40:43]
	s_nop 2
	ds_read_b128 v[40:43], v134 offset:7680
	v_mfma_f32_16x16x32_bf16 v[76:79], v[0:3], v[4:7], v[76:79]
	v_mfma_f32_16x16x32_bf16 v[72:75], v[12:15], v[4:7], v[72:75]
	v_mfma_f32_16x16x32_bf16 v[68:71], v[20:23], v[4:7], v[68:71]
	s_waitcnt lgkmcnt(0)
	v_mfma_f32_16x16x32_bf16 v[4:7], v[12:15], v[40:43], v[88:91]
	ds_read_b128 v[12:15], v149 offset:20544
	v_mfma_f32_16x16x32_bf16 v[84:87], v[0:3], v[40:43], v[84:87]
	s_nop 0
	ds_read_b128 v[88:91], v149 offset:23104
	v_mfma_f32_16x16x32_bf16 v[0:3], v[20:23], v[40:43], v[92:95]
	ds_read_b128 v[20:23], v134 offset:64
	s_nop 1
	ds_read_b128 v[92:95], v149 offset:25664
	s_waitcnt lgkmcnt(1)
	v_mfma_f32_16x16x32_bf16 v[56:59], v[12:15], v[20:23], v[8:11]
	s_nop 2
	ds_read_b128 v[8:11], v134 offset:2624
	v_mfma_f32_16x16x32_bf16 v[80:83], v[28:31], v[40:43], v[80:83]
	v_mfma_f32_16x16x32_bf16 v[48:51], v[128:131], v[20:23], v[32:35]
	s_waitcnt lgkmcnt(0)
	v_mfma_f32_16x16x32_bf16 v[40:43], v[12:15], v[8:11], v[64:67]
	v_mfma_f32_16x16x32_bf16 v[44:47], v[88:91], v[8:11], v[116:119]
	s_nop 1
	v_add_u32_e32 v64, s3, v133
	v_mfma_f32_16x16x32_bf16 v[32:35], v[92:95], v[8:11], v[120:123]
	v_mfma_f32_16x16x32_bf16 v[36:39], v[128:131], v[8:11], v[36:39]
	ds_read_b128 v[8:11], v134 offset:5184
	v_mfma_f32_16x16x32_bf16 v[52:55], v[92:95], v[20:23], v[24:27]
	s_waitcnt lgkmcnt(0)
	v_mfma_f32_16x16x32_bf16 v[24:27], v[12:15], v[8:11], v[76:79]
	v_mfma_f32_16x16x32_bf16 v[28:31], v[88:91], v[8:11], v[72:75]
	s_nop 2
	ds_read_b128 v[74:77], v134 offset:7744
	v_mfma_f32_16x16x32_bf16 v[60:63], v[88:91], v[20:23], v[16:19]
	v_or_b32_e32 v73, v64, v132
	v_cmp_lt_i32_e32 vcc, s22, v73
	s_and_b64 s[10:11], vcc, s[6:7]
	v_mfma_f32_16x16x32_bf16 v[16:19], v[92:95], v[8:11], v[68:71]
	v_mfma_f32_16x16x32_bf16 v[20:23], v[128:131], v[8:11], v[124:127]
	v_bfe_u32 v8, v64, 6, 6
	v_cvt_f32_ubyte0_e32 v65, v8
	v_mul_f32_e32 v66, v136, v65
	s_waitcnt lgkmcnt(0)
	v_mfma_f32_16x16x32_bf16 v[8:11], v[12:15], v[74:77], v[84:87]
	v_mul_f32_e32 v72, 0.15915494, v66
	v_mfma_f32_16x16x32_bf16 v[12:15], v[88:91], v[74:77], v[4:7]
	s_nop 2
	v_mul_f32_e32 v4, v137, v65
	v_mul_f32_e32 v5, v138, v65
	v_mul_f32_e32 v6, v139, v65
	v_mfma_f32_16x16x32_bf16 v[0:3], v[92:95], v[74:77], v[0:3]
	v_mul_f32_e32 v71, 0.15915494, v4
	v_mul_f32_e32 v70, 0.15915494, v5
	v_mul_f32_e32 v69, 0.15915494, v6
	v_mfma_f32_16x16x32_bf16 v[4:7], v[128:131], v[74:77], v[80:83]
	s_and_saveexec_b64 s[8:9], s[10:11]
	s_cbranch_execz .LBB0_253
	v_cos_f32_e32 v65, v70
	v_sin_f32_e32 v68, v70
	v_cos_f32_e32 v92, v69
	v_sin_f32_e32 v93, v69
	v_cos_f32_e32 v66, v72
	v_sin_f32_e32 v74, v72
	v_sin_f32_e32 v75, v71
	v_cos_f32_e32 v67, v71
	v_mul_f32_e32 v82, v68, v62
	v_mul_f32_e32 v86, v65, v62
	v_mov_b32_e32 v62, v59
	v_mul_f32_e32 v80, v65, v58
	v_mul_f32_e32 v84, v68, v58
	v_pk_mul_f32 v[58:59], v[92:93], v[62:63]
	v_mul_f32_e32 v90, v141, v50
	v_mul_f32_e32 v116, v140, v50
	v_mov_b32_e32 v81, v58
	v_mov_b32_e32 v83, v59
	v_mov_b32_e32 v58, v93
	v_mov_b32_e32 v59, v92
	v_mov_b32_e32 v50, v55
	v_pk_mul_f32 v[76:77], v[74:75], v[60:61]
	v_pk_mul_f32 v[60:61], v[66:67], v[60:61]
	v_pk_mul_f32 v[78:79], v[104:105], v[48:49]
	v_mul_f32_e32 v88, v140, v54
	v_mul_f32_e32 v94, v141, v54
	v_pk_mul_f32 v[58:59], v[58:59], v[62:63]
	v_pk_mul_f32 v[54:55], v[106:107], v[50:51]
	v_pk_mul_f32 v[50:51], v[108:109], v[50:51]
	v_pk_mul_f32 v[48:49], v[102:103], v[48:49]
	v_mov_b32_e32 v85, v58
	v_mov_b32_e32 v87, v59
	v_mov_b32_e32 v89, v54
	v_mov_b32_e32 v91, v55
	v_mov_b32_e32 v95, v50
	v_mov_b32_e32 v117, v51
	v_pk_fma_f32 v[66:67], v[66:67], v[56:57], v[76:77] neg_lo:[0,0,1] neg_hi:[0,0,1]
	v_pk_fma_f32 v[60:61], v[74:75], v[56:57], v[60:61]
	v_pk_fma_f32 v[74:75], v[102:103], v[52:53], v[78:79] neg_lo:[0,0,1] neg_hi:[0,0,1]
	v_pk_add_f32 v[58:59], v[80:81], v[82:83] neg_lo:[0,1] neg_hi:[0,1]
	v_pk_add_f32 v[62:63], v[84:85], v[86:87]
	v_pk_add_f32 v[54:55], v[88:89], v[90:91] neg_lo:[0,1] neg_hi:[0,1]
	v_pk_fma_f32 v[48:49], v[104:105], v[52:53], v[48:49]
	v_pk_add_f32 v[50:51], v[94:95], v[116:117]
	v_mov_b32_e32 v56, v66
	v_mov_b32_e32 v57, v67
	v_mov_b32_e32 v52, v74
	v_mov_b32_e32 v53, v75

.LBB0_437:
	s_and_b64 vcc, exec, s[6:7]
	s_cbranch_vccz .LBB0_738
	v_readlane_b32 s0, v253, 49
	v_readlane_b32 s1, v254, 46
	s_sub_i32 s0, s0, s1
	s_ashr_i32 s1, s0, 31
	v_readlane_b32 s2, v254, 0
	s_xor_b32 s1, s1, s2
	s_abs_i32 s0, s0
	v_readlane_b32 s2, v254, 2
	s_mul_hi_u32 s2, s0, s2
	v_readlane_b32 s5, v254, 1
	s_mul_i32 s3, s2, s5
	s_sub_i32 s0, s0, s3
	s_add_i32 s3, s2, 1
	s_sub_i32 s4, s0, s5
	s_cmp_ge_u32 s0, s5
	s_cselect_b32 s2, s3, s2
	s_cselect_b32 s0, s4, s0
	s_add_i32 s3, s2, 1
	s_cmp_ge_u32 s0, s5
	s_cselect_b32 s0, s3, s2
	s_xor_b32 s0, s0, s1
	s_sub_i32 s73, s0, s1
	v_readlane_b32 s0, v254, 52
	s_mulk_i32 s0, 0xe00
	s_cmp_lt_i32 s73, 1
	v_writelane_b32 v254, s0, 55
	s_movk_i32 s54, 0x6000
	s_mov_b64 s[20:21], 0x1000
	v_writelane_b32 v254, s1, 56
	s_cbranch_scc1 .LBB0_549
	v_readlane_b32 s0, v253, 50
	v_readlane_b32 s1, v254, 46
	s_getreg_b32 s0, hwreg(HW_REG_HW_ID, 16, 4)
	s_and_b32 s0, s0, 1
	s_cmp_eq_u32 s0, 1
	s_cselect_b64 s[0:1], -1, 0
	s_cmp_eq_u32 s73, 6
	s_cselect_b64 s[2:3], -1, 0
	s_and_b64 s[0:1], s[0:1], s[2:3]
	s_and_b64 s[0:1], s[0:1], exec
	v_readlane_b32 s22, v254, 52
	s_cselect_b32 s77, 2, 0
	s_lshl_b32 s0, s22, 3
	v_writelane_b32 v254, s0, 57
	v_cvt_f32_u32_e32 v0, s73
	v_readlane_b32 s2, v254, 55
	s_mov_b32 s4, s2
	v_readlane_b32 s3, v254, 56
	v_writelane_b32 v254, s4, 55
	s_mov_b32 s3, s51
	s_lshl_b32 s50, s22, 10
	v_writelane_b32 v254, s5, 56
	v_readlane_b32 s4, v252, 29
	s_lshl_b32 s0, s22, 9
	s_lshl_b64 s[2:3], s[2:3], 2
	v_readlane_b32 s6, v252, 31
	v_readlane_b32 s7, v252, 32
	s_add_u32 s80, s6, s2
	v_readlane_b32 s8, v252, 33
	s_addc_u32 s81, s7, s3
	s_lshl_b64 s[2:3], s[50:51], 2
	v_readlane_b32 s5, v252, 30
	v_readlane_b32 s9, v252, 34
	s_add_u32 s4, s8, s2
	v_rcp_iflag_f32_e32 v0, v0
	v_readlane_b32 s12, v252, 37
	s_addc_u32 s5, s9, s3
	s_mov_b32 s1, s51
	v_readlane_b32 s13, v252, 38
	s_add_u32 s86, s12, s2
	v_readlane_b32 s16, v252, 41
	v_writelane_b32 v254, s4, 59
	s_addc_u32 s87, s13, s3
	s_lshl_b64 s[0:1], s[0:1], 2
	v_readlane_b32 s17, v252, 42
	v_writelane_b32 v254, s5, 60
	s_add_u32 s4, s16, s0
	v_mul_f32_e32 v0, 0x4f7ffffe, v0
	v_readlane_b32 s18, v252, 43
	s_addc_u32 s5, s17, s1
	v_cvt_u32_f32_e32 v0, v0
	v_readlane_b32 s10, v252, 35
	v_readlane_b32 s11, v252, 36
	v_readlane_b32 s14, v252, 39
	v_readlane_b32 s15, v252, 40
	v_readlane_b32 s19, v252, 44
	v_writelane_b32 v254, s4, 61
	s_add_u32 s78, s18, s0
	s_addc_u32 s79, s19, s1
	v_writelane_b32 v254, s5, 62
	v_readlane_b32 s4, v252, 45
	v_readlane_b32 s5, v252, 46
	s_add_u32 s74, s4, s2
	s_addc_u32 s75, s5, s3
	s_sub_i32 s0, 0, s73
	v_readfirstlane_b32 s1, v0
	s_mul_i32 s0, s0, s1
	s_mul_hi_u32 s0, s1, s0
	s_mov_b32 s76, 0
	s_lshl_b32 s83, s22, 2
	s_add_i32 s82, s1, s0
	v_readlane_b32 s6, v252, 47
	v_readlane_b32 s7, v252, 48
	v_readlane_b32 s8, v252, 49
	v_readlane_b32 s9, v252, 50
	v_readlane_b32 s10, v252, 51
	v_readlane_b32 s11, v252, 52
	v_readlane_b32 s12, v252, 53
	v_readlane_b32 s13, v252, 54
	v_readlane_b32 s14, v252, 55
	v_readlane_b32 s15, v252, 56
	v_readlane_b32 s16, v252, 57
	v_readlane_b32 s17, v252, 58
	v_readlane_b32 s18, v252, 59
	v_readlane_b32 s19, v252, 60
	s_branch .LBB0_442

.LBB0_539:
	v_and_b32_e32 v196, 0xc0, v174
	v_and_b32_e32 v152, 60, v174
	v_add_u32_e32 v196, v196, v247
	v_add_u32_e32 v152, v152, v247
	ds_read_b128 v[64:67], v196 offset:20480
	ds_read_b128 v[68:71], v196 offset:20496
	ds_read_b128 v[72:75], v196 offset:20512
	ds_read_b128 v[76:79], v196 offset:20528
	v_mov_b32_e32 v144, 0
	v_mov_b32_e32 v146, 0
	v_mov_b32_e32 v148, 0
	v_mov_b32_e32 v150, 0
	s_and_saveexec_b64 s[22:23], s[4:5]
	ds_read_b32 v144, v152 offset:8192
	ds_read_b32 v146, v152 offset:8256
	ds_read_b32 v148, v152 offset:8320
	ds_read_b32 v150, v152 offset:8384
	s_or_b64 exec, exec, s[22:23]
	ds_read_b128 v[80:83], v196 offset:12288
	ds_read_b128 v[84:87], v196 offset:12304
	ds_read_b128 v[88:91], v196 offset:12320
	ds_read_b128 v[92:95], v196 offset:12336
	s_waitcnt lgkmcnt(4)
	v_pk_mul_f32 v[152:153], v[0:1], v[64:65]
	v_pk_mul_f32 v[154:155], v[16:17], v[64:65]
	v_pk_mul_f32 v[156:157], v[32:33], v[64:65]
	v_pk_mul_f32 v[158:159], v[48:49], v[64:65]
	ds_read_b128 v[96:99], v196 offset:16384
	ds_read_b128 v[100:103], v196 offset:16400
	v_pk_fma_f32 v[152:153], v[2:3], v[66:67], v[152:153]
	v_pk_fma_f32 v[154:155], v[18:19], v[66:67], v[154:155]
	v_pk_fma_f32 v[156:157], v[34:35], v[66:67], v[156:157]
	v_pk_fma_f32 v[158:159], v[50:51], v[66:67], v[158:159]
	ds_read_b128 v[104:107], v196 offset:16416
	ds_read_b128 v[108:111], v196 offset:16432
	v_pk_fma_f32 v[152:153], v[4:5], v[68:69], v[152:153]
	v_pk_fma_f32 v[154:155], v[20:21], v[68:69], v[154:155]
	v_pk_fma_f32 v[156:157], v[36:37], v[68:69], v[156:157]
	v_pk_fma_f32 v[158:159], v[52:53], v[68:69], v[158:159]
	ds_read_b128 v[112:115], v196 offset:4096
	ds_read_b128 v[116:119], v196 offset:4112
	v_pk_fma_f32 v[152:153], v[6:7], v[70:71], v[152:153]
	v_pk_fma_f32 v[154:155], v[22:23], v[70:71], v[154:155]
	v_pk_fma_f32 v[156:157], v[38:39], v[70:71], v[156:157]
	v_pk_fma_f32 v[158:159], v[54:55], v[70:71], v[158:159]
	ds_read_b128 v[120:123], v196 offset:4128
	ds_read_b128 v[124:127], v196 offset:4144
	v_pk_fma_f32 v[152:153], v[8:9], v[72:73], v[152:153]
	v_pk_fma_f32 v[154:155], v[24:25], v[72:73], v[154:155]
	v_pk_fma_f32 v[156:157], v[40:41], v[72:73], v[156:157]
	v_pk_fma_f32 v[158:159], v[56:57], v[72:73], v[158:159]
	ds_read_b128 v[128:131], v196 offset:0
	ds_read_b128 v[132:135], v196 offset:16
	v_pk_fma_f32 v[152:153], v[10:11], v[74:75], v[152:153]
	v_pk_fma_f32 v[154:155], v[26:27], v[74:75], v[154:155]
	v_pk_fma_f32 v[156:157], v[42:43], v[74:75], v[156:157]
	v_pk_fma_f32 v[158:159], v[58:59], v[74:75], v[158:159]
	ds_read_b128 v[136:139], v196 offset:32
	ds_read_b128 v[140:143], v196 offset:48
	v_pk_fma_f32 v[152:153], v[12:13], v[76:77], v[152:153]
	v_pk_fma_f32 v[154:155], v[28:29], v[76:77], v[154:155]
	v_pk_fma_f32 v[156:157], v[44:45], v[76:77], v[156:157]
	v_pk_fma_f32 v[158:159], v[60:61], v[76:77], v[158:159]
	v_pk_fma_f32 v[152:153], v[14:15], v[78:79], v[152:153]
	v_pk_fma_f32 v[154:155], v[30:31], v[78:79], v[154:155]
	v_pk_fma_f32 v[156:157], v[46:47], v[78:79], v[156:157]
	v_pk_fma_f32 v[158:159], v[62:63], v[78:79], v[158:159]
	v_add_f32_e32 v152, v152, v153
	v_add_f32_e32 v154, v154, v155
	v_add_f32_e32 v156, v156, v157
	v_add_f32_e32 v158, v158, v159
	s_nop 0
	v_permlane16_swap_b32_e32 v152, v154
	v_permlane16_swap_b32_e32 v156, v158
	v_add_f32_e32 v152, v152, v154
	v_add_f32_e32 v156, v156, v158
	s_nop 1
	v_permlane32_swap_b32_e32 v152, v156
	v_add_f32_e32 v152, v152, v156
	v_mov_b32_e32 v154, v152
	s_nop 1
	v_permlane16_swap_b32_e32 v152, v154
	v_mov_b32_e32 v156, v152
	v_mov_b32_e32 v158, v154
	s_nop 1
	v_permlane32_swap_b32_e32 v152, v156
	v_permlane32_swap_b32_e32 v154, v158
	s_waitcnt lgkmcnt(0)
	s_cmp_eq_u64 s[4:5], 0
	s_cbranch_scc1 .Lscan_T
	v_pk_mul_f32 v[0:1], v[0:1], v[80:81]
	v_pk_mul_f32 v[16:17], v[16:17], v[80:81]
	v_pk_mul_f32 v[32:33], v[32:33], v[80:81]
	v_pk_mul_f32 v[48:49], v[48:49], v[80:81]
	v_pk_fma_f32 v[0:1], v[152:153], v[96:97], v[0:1] op_sel_hi:[0,1,1] neg_lo:[1,0,0] neg_hi:[1,0,0]
	v_pk_fma_f32 v[16:17], v[154:155], v[96:97], v[16:17] op_sel_hi:[0,1,1] neg_lo:[1,0,0] neg_hi:[1,0,0]
	v_pk_fma_f32 v[32:33], v[156:157], v[96:97], v[32:33] op_sel_hi:[0,1,1] neg_lo:[1,0,0] neg_hi:[1,0,0]
	v_pk_fma_f32 v[48:49], v[158:159], v[96:97], v[48:49] op_sel_hi:[0,1,1] neg_lo:[1,0,0] neg_hi:[1,0,0]
	v_pk_fma_f32 v[0:1], v[144:145], v[112:113], v[0:1] op_sel_hi:[0,1,1]
	v_pk_fma_f32 v[16:17], v[146:147], v[112:113], v[16:17] op_sel_hi:[0,1,1]
	v_pk_fma_f32 v[32:33], v[148:149], v[112:113], v[32:33] op_sel_hi:[0,1,1]
	v_pk_fma_f32 v[48:49], v[150:151], v[112:113], v[48:49] op_sel_hi:[0,1,1]
	v_pk_mul_f32 v[230:231], v[0:1], v[128:129]
	v_pk_mul_f32 v[232:233], v[16:17], v[128:129]
	v_pk_mul_f32 v[248:249], v[32:33], v[128:129]
	v_pk_mul_f32 v[250:251], v[48:49], v[128:129]
	v_pk_mul_f32 v[2:3], v[2:3], v[82:83]
	v_pk_mul_f32 v[18:19], v[18:19], v[82:83]
	v_pk_mul_f32 v[34:35], v[34:35], v[82:83]
	v_pk_mul_f32 v[50:51], v[50:51], v[82:83]
	v_pk_fma_f32 v[2:3], v[152:153], v[98:99], v[2:3] op_sel_hi:[0,1,1] neg_lo:[1,0,0] neg_hi:[1,0,0]
	v_pk_fma_f32 v[18:19], v[154:155], v[98:99], v[18:19] op_sel_hi:[0,1,1] neg_lo:[1,0,0] neg_hi:[1,0,0]
	v_pk_fma_f32 v[34:35], v[156:157], v[98:99], v[34:35] op_sel_hi:[0,1,1] neg_lo:[1,0,0] neg_hi:[1,0,0]
	v_pk_fma_f32 v[50:51], v[158:159], v[98:99], v[50:51] op_sel_hi:[0,1,1] neg_lo:[1,0,0] neg_hi:[1,0,0]
	v_pk_fma_f32 v[2:3], v[144:145], v[114:115], v[2:3] op_sel_hi:[0,1,1]
	v_pk_fma_f32 v[18:19], v[146:147], v[114:115], v[18:19] op_sel_hi:[0,1,1]
	v_pk_fma_f32 v[34:35], v[148:149], v[114:115], v[34:35] op_sel_hi:[0,1,1]
	v_pk_fma_f32 v[50:51], v[150:151], v[114:115], v[50:51] op_sel_hi:[0,1,1]
	v_pk_fma_f32 v[230:231], v[2:3], v[130:131], v[230:231]
	v_pk_fma_f32 v[232:233], v[18:19], v[130:131], v[232:233]
	v_pk_fma_f32 v[248:249], v[34:35], v[130:131], v[248:249]
	v_pk_fma_f32 v[250:251], v[50:51], v[130:131], v[250:251]
	v_pk_mul_f32 v[4:5], v[4:5], v[84:85]
	v_pk_mul_f32 v[20:21], v[20:21], v[84:85]
	v_pk_mul_f32 v[36:37], v[36:37], v[84:85]
	v_pk_mul_f32 v[52:53], v[52:53], v[84:85]
	v_pk_fma_f32 v[4:5], v[152:153], v[100:101], v[4:5] op_sel_hi:[0,1,1] neg_lo:[1,0,0] neg_hi:[1,0,0]
	v_pk_fma_f32 v[20:21], v[154:155], v[100:101], v[20:21] op_sel_hi:[0,1,1] neg_lo:[1,0,0] neg_hi:[1,0,0]
	v_pk_fma_f32 v[36:37], v[156:157], v[100:101], v[36:37] op_sel_hi:[0,1,1] neg_lo:[1,0,0] neg_hi:[1,0,0]
	v_pk_fma_f32 v[52:53], v[158:159], v[100:101], v[52:53] op_sel_hi:[0,1,1] neg_lo:[1,0,0] neg_hi:[1,0,0]
	v_pk_fma_f32 v[4:5], v[144:145], v[116:117], v[4:5] op_sel_hi:[0,1,1]
	v_pk_fma_f32 v[20:21], v[146:147], v[116:117], v[20:21] op_sel_hi:[0,1,1]
	v_pk_fma_f32 v[36:37], v[148:149], v[116:117], v[36:37] op_sel_hi:[0,1,1]
	v_pk_fma_f32 v[52:53], v[150:151], v[116:117], v[52:53] op_sel_hi:[0,1,1]
	v_pk_fma_f32 v[230:231], v[4:5], v[132:133], v[230:231]
	v_pk_fma_f32 v[232:233], v[20:21], v[132:133], v[232:233]
	v_pk_fma_f32 v[248:249], v[36:37], v[132:133], v[248:249]
	v_pk_fma_f32 v[250:251], v[52:53], v[132:133], v[250:251]
	v_pk_mul_f32 v[6:7], v[6:7], v[86:87]
	v_pk_mul_f32 v[22:23], v[22:23], v[86:87]
	v_pk_mul_f32 v[38:39], v[38:39], v[86:87]
	v_pk_mul_f32 v[54:55], v[54:55], v[86:87]
	v_pk_fma_f32 v[6:7], v[152:153], v[102:103], v[6:7] op_sel_hi:[0,1,1] neg_lo:[1,0,0] neg_hi:[1,0,0]
	v_pk_fma_f32 v[22:23], v[154:155], v[102:103], v[22:23] op_sel_hi:[0,1,1] neg_lo:[1,0,0] neg_hi:[1,0,0]
	v_pk_fma_f32 v[38:39], v[156:157], v[102:103], v[38:39] op_sel_hi:[0,1,1] neg_lo:[1,0,0] neg_hi:[1,0,0]
	v_pk_fma_f32 v[54:55], v[158:159], v[102:103], v[54:55] op_sel_hi:[0,1,1] neg_lo:[1,0,0] neg_hi:[1,0,0]
	v_pk_fma_f32 v[6:7], v[144:145], v[118:119], v[6:7] op_sel_hi:[0,1,1]
	v_pk_fma_f32 v[22:23], v[146:147], v[118:119], v[22:23] op_sel_hi:[0,1,1]
	v_pk_fma_f32 v[38:39], v[148:149], v[118:119], v[38:39] op_sel_hi:[0,1,1]
	v_pk_fma_f32 v[54:55], v[150:151], v[118:119], v[54:55] op_sel_hi:[0,1,1]
	v_pk_fma_f32 v[230:231], v[6:7], v[134:135], v[230:231]
	v_pk_fma_f32 v[232:233], v[22:23], v[134:135], v[232:233]
	v_pk_fma_f32 v[248:249], v[38:39], v[134:135], v[248:249]
	v_pk_fma_f32 v[250:251], v[54:55], v[134:135], v[250:251]
	v_pk_mul_f32 v[8:9], v[8:9], v[88:89]
	v_pk_mul_f32 v[24:25], v[24:25], v[88:89]
	v_pk_mul_f32 v[40:41], v[40:41], v[88:89]
	v_pk_mul_f32 v[56:57], v[56:57], v[88:89]
	v_pk_fma_f32 v[8:9], v[152:153], v[104:105], v[8:9] op_sel_hi:[0,1,1] neg_lo:[1,0,0] neg_hi:[1,0,0]
	v_pk_fma_f32 v[24:25], v[154:155], v[104:105], v[24:25] op_sel_hi:[0,1,1] neg_lo:[1,0,0] neg_hi:[1,0,0]
	v_pk_fma_f32 v[40:41], v[156:157], v[104:105], v[40:41] op_sel_hi:[0,1,1] neg_lo:[1,0,0] neg_hi:[1,0,0]
	v_pk_fma_f32 v[56:57], v[158:159], v[104:105], v[56:57] op_sel_hi:[0,1,1] neg_lo:[1,0,0] neg_hi:[1,0,0]
	v_pk_fma_f32 v[8:9], v[144:145], v[120:121], v[8:9] op_sel_hi:[0,1,1]
	v_pk_fma_f32 v[24:25], v[146:147], v[120:121], v[24:25] op_sel_hi:[0,1,1]
	v_pk_fma_f32 v[40:41], v[148:149], v[120:121], v[40:41] op_sel_hi:[0,1,1]
	v_pk_fma_f32 v[56:57], v[150:151], v[120:121], v[56:57] op_sel_hi:[0,1,1]
	v_pk_fma_f32 v[230:231], v[8:9], v[136:137], v[230:231]
	v_pk_fma_f32 v[232:233], v[24:25], v[136:137], v[232:233]
	v_pk_fma_f32 v[248:249], v[40:41], v[136:137], v[248:249]
	v_pk_fma_f32 v[250:251], v[56:57], v[136:137], v[250:251]
	v_pk_mul_f32 v[10:11], v[10:11], v[90:91]
	v_pk_mul_f32 v[26:27], v[26:27], v[90:91]
	v_pk_mul_f32 v[42:43], v[42:43], v[90:91]
	v_pk_mul_f32 v[58:59], v[58:59], v[90:91]
	v_pk_fma_f32 v[10:11], v[152:153], v[106:107], v[10:11] op_sel_hi:[0,1,1] neg_lo:[1,0,0] neg_hi:[1,0,0]
	v_pk_fma_f32 v[26:27], v[154:155], v[106:107], v[26:27] op_sel_hi:[0,1,1] neg_lo:[1,0,0] neg_hi:[1,0,0]
	v_pk_fma_f32 v[42:43], v[156:157], v[106:107], v[42:43] op_sel_hi:[0,1,1] neg_lo:[1,0,0] neg_hi:[1,0,0]
	v_pk_fma_f32 v[58:59], v[158:159], v[106:107], v[58:59] op_sel_hi:[0,1,1] neg_lo:[1,0,0] neg_hi:[1,0,0]
	v_pk_fma_f32 v[10:11], v[144:145], v[122:123], v[10:11] op_sel_hi:[0,1,1]
	v_pk_fma_f32 v[26:27], v[146:147], v[122:123], v[26:27] op_sel_hi:[0,1,1]
	v_pk_fma_f32 v[42:43], v[148:149], v[122:123], v[42:43] op_sel_hi:[0,1,1]
	v_pk_fma_f32 v[58:59], v[150:151], v[122:123], v[58:59] op_sel_hi:[0,1,1]
	v_pk_fma_f32 v[230:231], v[10:11], v[138:139], v[230:231]
	v_pk_fma_f32 v[232:233], v[26:27], v[138:139], v[232:233]
	v_pk_fma_f32 v[248:249], v[42:43], v[138:139], v[248:249]
	v_pk_fma_f32 v[250:251], v[58:59], v[138:139], v[250:251]
	v_pk_mul_f32 v[12:13], v[12:13], v[92:93]
	v_pk_mul_f32 v[28:29], v[28:29], v[92:93]
	v_pk_mul_f32 v[44:45], v[44:45], v[92:93]
	v_pk_mul_f32 v[60:61], v[60:61], v[92:93]
	v_pk_fma_f32 v[12:13], v[152:153], v[108:109], v[12:13] op_sel_hi:[0,1,1] neg_lo:[1,0,0] neg_hi:[1,0,0]
	v_pk_fma_f32 v[28:29], v[154:155], v[108:109], v[28:29] op_sel_hi:[0,1,1] neg_lo:[1,0,0] neg_hi:[1,0,0]
	v_pk_fma_f32 v[44:45], v[156:157], v[108:109], v[44:45] op_sel_hi:[0,1,1] neg_lo:[1,0,0] neg_hi:[1,0,0]
	v_pk_fma_f32 v[60:61], v[158:159], v[108:109], v[60:61] op_sel_hi:[0,1,1] neg_lo:[1,0,0] neg_hi:[1,0,0]
	v_pk_fma_f32 v[12:13], v[144:145], v[124:125], v[12:13] op_sel_hi:[0,1,1]
	v_pk_fma_f32 v[28:29], v[146:147], v[124:125], v[28:29] op_sel_hi:[0,1,1]
	v_pk_fma_f32 v[44:45], v[148:149], v[124:125], v[44:45] op_sel_hi:[0,1,1]
	v_pk_fma_f32 v[60:61], v[150:151], v[124:125], v[60:61] op_sel_hi:[0,1,1]
	v_pk_fma_f32 v[230:231], v[12:13], v[140:141], v[230:231]
	v_pk_fma_f32 v[232:233], v[28:29], v[140:141], v[232:233]
	v_pk_fma_f32 v[248:249], v[44:45], v[140:141], v[248:249]
	v_pk_fma_f32 v[250:251], v[60:61], v[140:141], v[250:251]
	v_pk_mul_f32 v[14:15], v[14:15], v[94:95]
	v_pk_mul_f32 v[30:31], v[30:31], v[94:95]
	v_pk_mul_f32 v[46:47], v[46:47], v[94:95]
	v_pk_mul_f32 v[62:63], v[62:63], v[94:95]
	v_pk_fma_f32 v[14:15], v[152:153], v[110:111], v[14:15] op_sel_hi:[0,1,1] neg_lo:[1,0,0] neg_hi:[1,0,0]
	v_pk_fma_f32 v[30:31], v[154:155], v[110:111], v[30:31] op_sel_hi:[0,1,1] neg_lo:[1,0,0] neg_hi:[1,0,0]
	v_pk_fma_f32 v[46:47], v[156:157], v[110:111], v[46:47] op_sel_hi:[0,1,1] neg_lo:[1,0,0] neg_hi:[1,0,0]
	v_pk_fma_f32 v[62:63], v[158:159], v[110:111], v[62:63] op_sel_hi:[0,1,1] neg_lo:[1,0,0] neg_hi:[1,0,0]
	v_pk_fma_f32 v[14:15], v[144:145], v[126:127], v[14:15] op_sel_hi:[0,1,1]
	v_pk_fma_f32 v[30:31], v[146:147], v[126:127], v[30:31] op_sel_hi:[0,1,1]
	v_pk_fma_f32 v[46:47], v[148:149], v[126:127], v[46:47] op_sel_hi:[0,1,1]
	v_pk_fma_f32 v[62:63], v[150:151], v[126:127], v[62:63] op_sel_hi:[0,1,1]
	v_pk_fma_f32 v[230:231], v[14:15], v[142:143], v[230:231]
	v_pk_fma_f32 v[232:233], v[30:31], v[142:143], v[232:233]
	v_pk_fma_f32 v[248:249], v[46:47], v[142:143], v[248:249]
	v_pk_fma_f32 v[250:251], v[62:63], v[142:143], v[250:251]
	s_branch .Lscan_join
.Lscan_T:
	v_pk_mul_f32 v[0:1], v[0:1], v[80:81]
	v_pk_mul_f32 v[16:17], v[16:17], v[80:81]
	v_pk_mul_f32 v[32:33], v[32:33], v[80:81]
	v_pk_mul_f32 v[48:49], v[48:49], v[80:81]
	v_pk_fma_f32 v[0:1], v[152:153], v[96:97], v[0:1] op_sel_hi:[0,1,1] neg_lo:[1,0,0] neg_hi:[1,0,0]
	v_pk_fma_f32 v[16:17], v[154:155], v[96:97], v[16:17] op_sel_hi:[0,1,1] neg_lo:[1,0,0] neg_hi:[1,0,0]
	v_pk_fma_f32 v[32:33], v[156:157], v[96:97], v[32:33] op_sel_hi:[0,1,1] neg_lo:[1,0,0] neg_hi:[1,0,0]
	v_pk_fma_f32 v[48:49], v[158:159], v[96:97], v[48:49] op_sel_hi:[0,1,1] neg_lo:[1,0,0] neg_hi:[1,0,0]
	v_pk_mul_f32 v[230:231], v[0:1], v[128:129]
	v_pk_mul_f32 v[232:233], v[16:17], v[128:129]
	v_pk_mul_f32 v[248:249], v[32:33], v[128:129]
	v_pk_mul_f32 v[250:251], v[48:49], v[128:129]
	v_pk_mul_f32 v[2:3], v[2:3], v[82:83]
	v_pk_mul_f32 v[18:19], v[18:19], v[82:83]
	v_pk_mul_f32 v[34:35], v[34:35], v[82:83]
	v_pk_mul_f32 v[50:51], v[50:51], v[82:83]
	v_pk_fma_f32 v[2:3], v[152:153], v[98:99], v[2:3] op_sel_hi:[0,1,1] neg_lo:[1,0,0] neg_hi:[1,0,0]
	v_pk_fma_f32 v[18:19], v[154:155], v[98:99], v[18:19] op_sel_hi:[0,1,1] neg_lo:[1,0,0] neg_hi:[1,0,0]
	v_pk_fma_f32 v[34:35], v[156:157], v[98:99], v[34:35] op_sel_hi:[0,1,1] neg_lo:[1,0,0] neg_hi:[1,0,0]
	v_pk_fma_f32 v[50:51], v[158:159], v[98:99], v[50:51] op_sel_hi:[0,1,1] neg_lo:[1,0,0] neg_hi:[1,0,0]
	v_pk_fma_f32 v[230:231], v[2:3], v[130:131], v[230:231]
	v_pk_fma_f32 v[232:233], v[18:19], v[130:131], v[232:233]
	v_pk_fma_f32 v[248:249], v[34:35], v[130:131], v[248:249]
	v_pk_fma_f32 v[250:251], v[50:51], v[130:131], v[250:251]
	v_pk_mul_f32 v[4:5], v[4:5], v[84:85]
	v_pk_mul_f32 v[20:21], v[20:21], v[84:85]
	v_pk_mul_f32 v[36:37], v[36:37], v[84:85]
	v_pk_mul_f32 v[52:53], v[52:53], v[84:85]
	v_pk_fma_f32 v[4:5], v[152:153], v[100:101], v[4:5] op_sel_hi:[0,1,1] neg_lo:[1,0,0] neg_hi:[1,0,0]
	v_pk_fma_f32 v[20:21], v[154:155], v[100:101], v[20:21] op_sel_hi:[0,1,1] neg_lo:[1,0,0] neg_hi:[1,0,0]
	v_pk_fma_f32 v[36:37], v[156:157], v[100:101], v[36:37] op_sel_hi:[0,1,1] neg_lo:[1,0,0] neg_hi:[1,0,0]
	v_pk_fma_f32 v[52:53], v[158:159], v[100:101], v[52:53] op_sel_hi:[0,1,1] neg_lo:[1,0,0] neg_hi:[1,0,0]
	v_pk_fma_f32 v[230:231], v[4:5], v[132:133], v[230:231]
	v_pk_fma_f32 v[232:233], v[20:21], v[132:133], v[232:233]
	v_pk_fma_f32 v[248:249], v[36:37], v[132:133], v[248:249]
	v_pk_fma_f32 v[250:251], v[52:53], v[132:133], v[250:251]
	v_pk_mul_f32 v[6:7], v[6:7], v[86:87]
	v_pk_mul_f32 v[22:23], v[22:23], v[86:87]
	v_pk_mul_f32 v[38:39], v[38:39], v[86:87]
	v_pk_mul_f32 v[54:55], v[54:55], v[86:87]
	v_pk_fma_f32 v[6:7], v[152:153], v[102:103], v[6:7] op_sel_hi:[0,1,1] neg_lo:[1,0,0] neg_hi:[1,0,0]
	v_pk_fma_f32 v[22:23], v[154:155], v[102:103], v[22:23] op_sel_hi:[0,1,1] neg_lo:[1,0,0] neg_hi:[1,0,0]
	v_pk_fma_f32 v[38:39], v[156:157], v[102:103], v[38:39] op_sel_hi:[0,1,1] neg_lo:[1,0,0] neg_hi:[1,0,0]
	v_pk_fma_f32 v[54:55], v[158:159], v[102:103], v[54:55] op_sel_hi:[0,1,1] neg_lo:[1,0,0] neg_hi:[1,0,0]
	v_pk_fma_f32 v[230:231], v[6:7], v[134:135], v[230:231]
	v_pk_fma_f32 v[232:233], v[22:23], v[134:135], v[232:233]
	v_pk_fma_f32 v[248:249], v[38:39], v[134:135], v[248:249]
	v_pk_fma_f32 v[250:251], v[54:55], v[134:135], v[250:251]
	v_pk_mul_f32 v[8:9], v[8:9], v[88:89]
	v_pk_mul_f32 v[24:25], v[24:25], v[88:89]
	v_pk_mul_f32 v[40:41], v[40:41], v[88:89]
	v_pk_mul_f32 v[56:57], v[56:57], v[88:89]
	v_pk_fma_f32 v[8:9], v[152:153], v[104:105], v[8:9] op_sel_hi:[0,1,1] neg_lo:[1,0,0] neg_hi:[1,0,0]
	v_pk_fma_f32 v[24:25], v[154:155], v[104:105], v[24:25] op_sel_hi:[0,1,1] neg_lo:[1,0,0] neg_hi:[1,0,0]
	v_pk_fma_f32 v[40:41], v[156:157], v[104:105], v[40:41] op_sel_hi:[0,1,1] neg_lo:[1,0,0] neg_hi:[1,0,0]
	v_pk_fma_f32 v[56:57], v[158:159], v[104:105], v[56:57] op_sel_hi:[0,1,1] neg_lo:[1,0,0] neg_hi:[1,0,0]
	v_pk_fma_f32 v[230:231], v[8:9], v[136:137], v[230:231]
	v_pk_fma_f32 v[232:233], v[24:25], v[136:137], v[232:233]
	v_pk_fma_f32 v[248:249], v[40:41], v[136:137], v[248:249]
	v_pk_fma_f32 v[250:251], v[56:57], v[136:137], v[250:251]
	v_pk_mul_f32 v[10:11], v[10:11], v[90:91]
	v_pk_mul_f32 v[26:27], v[26:27], v[90:91]
	v_pk_mul_f32 v[42:43], v[42:43], v[90:91]
	v_pk_mul_f32 v[58:59], v[58:59], v[90:91]
	v_pk_fma_f32 v[10:11], v[152:153], v[106:107], v[10:11] op_sel_hi:[0,1,1] neg_lo:[1,0,0] neg_hi:[1,0,0]
	v_pk_fma_f32 v[26:27], v[154:155], v[106:107], v[26:27] op_sel_hi:[0,1,1] neg_lo:[1,0,0] neg_hi:[1,0,0]
	v_pk_fma_f32 v[42:43], v[156:157], v[106:107], v[42:43] op_sel_hi:[0,1,1] neg_lo:[1,0,0] neg_hi:[1,0,0]
	v_pk_fma_f32 v[58:59], v[158:159], v[106:107], v[58:59] op_sel_hi:[0,1,1] neg_lo:[1,0,0] neg_hi:[1,0,0]
	v_pk_fma_f32 v[230:231], v[10:11], v[138:139], v[230:231]
	v_pk_fma_f32 v[232:233], v[26:27], v[138:139], v[232:233]
	v_pk_fma_f32 v[248:249], v[42:43], v[138:139], v[248:249]
	v_pk_fma_f32 v[250:251], v[58:59], v[138:139], v[250:251]
	v_pk_mul_f32 v[12:13], v[12:13], v[92:93]
	v_pk_mul_f32 v[28:29], v[28:29], v[92:93]
	v_pk_mul_f32 v[44:45], v[44:45], v[92:93]
	v_pk_mul_f32 v[60:61], v[60:61], v[92:93]
	v_pk_fma_f32 v[12:13], v[152:153], v[108:109], v[12:13] op_sel_hi:[0,1,1] neg_lo:[1,0,0] neg_hi:[1,0,0]
	v_pk_fma_f32 v[28:29], v[154:155], v[108:109], v[28:29] op_sel_hi:[0,1,1] neg_lo:[1,0,0] neg_hi:[1,0,0]
	v_pk_fma_f32 v[44:45], v[156:157], v[108:109], v[44:45] op_sel_hi:[0,1,1] neg_lo:[1,0,0] neg_hi:[1,0,0]
	v_pk_fma_f32 v[60:61], v[158:159], v[108:109], v[60:61] op_sel_hi:[0,1,1] neg_lo:[1,0,0] neg_hi:[1,0,0]
	v_pk_fma_f32 v[230:231], v[12:13], v[140:141], v[230:231]
	v_pk_fma_f32 v[232:233], v[28:29], v[140:141], v[232:233]
	v_pk_fma_f32 v[248:249], v[44:45], v[140:141], v[248:249]
	v_pk_fma_f32 v[250:251], v[60:61], v[140:141], v[250:251]
	v_pk_mul_f32 v[14:15], v[14:15], v[94:95]
	v_pk_mul_f32 v[30:31], v[30:31], v[94:95]
	v_pk_mul_f32 v[46:47], v[46:47], v[94:95]
	v_pk_mul_f32 v[62:63], v[62:63], v[94:95]
	v_pk_fma_f32 v[14:15], v[152:153], v[110:111], v[14:15] op_sel_hi:[0,1,1] neg_lo:[1,0,0] neg_hi:[1,0,0]
	v_pk_fma_f32 v[30:31], v[154:155], v[110:111], v[30:31] op_sel_hi:[0,1,1] neg_lo:[1,0,0] neg_hi:[1,0,0]
	v_pk_fma_f32 v[46:47], v[156:157], v[110:111], v[46:47] op_sel_hi:[0,1,1] neg_lo:[1,0,0] neg_hi:[1,0,0]
	v_pk_fma_f32 v[62:63], v[158:159], v[110:111], v[62:63] op_sel_hi:[0,1,1] neg_lo:[1,0,0] neg_hi:[1,0,0]
	v_pk_fma_f32 v[230:231], v[14:15], v[142:143], v[230:231]
	v_pk_fma_f32 v[232:233], v[30:31], v[142:143], v[232:233]
	v_pk_fma_f32 v[248:249], v[46:47], v[142:143], v[248:249]
	v_pk_fma_f32 v[250:251], v[62:63], v[142:143], v[250:251]
.Lscan_join:
	s_add_i32 s22, s30, s2
	v_mov_b32_e32 v64, s3
	v_mov_b32_e32 v65, s22
	v_cndmask_b32_e64 v64, v64, v65, s[14:15]
	v_add_f32_e32 v230, v230, v231
	v_add_f32_e32 v232, v232, v233
	v_add_f32_e32 v248, v248, v249
	v_add_f32_e32 v250, v250, v251
	s_nop 0
	v_permlane16_swap_b32_e32 v230, v232
	v_permlane16_swap_b32_e32 v248, v250
	v_add_f32_e32 v230, v230, v232
	v_add_f32_e32 v248, v248, v250
	s_nop 1
	v_permlane32_swap_b32_e32 v230, v248
	v_add_f32_e32 v66, v230, v248
	s_and_saveexec_b64 s[22:23], s[0:1]
	s_xor_b64 s[22:23], exec, s[22:23]
	s_cbranch_execz .LBB0_543
	v_ashrrev_i32_e32 v65, 31, v64
	v_lshlrev_b64 v[64:65], 12, v[64:65]
	v_lshl_add_u64 v[64:65], v[190:191], 0, v[64:65]
	global_store_dword v[64:65], v66, off
